# strategy 8: out-proj half-step leading ds_reads issued under the DMA issue block, on top of per-fragment lgkmcnt waits
# speedup vs baseline: 1.0012x; 1.0012x over previous
.LBB0_80:
	s_andn2_b64 vcc, exec, s[38:39]
	s_waitcnt lgkmcnt(6)
	v_mfma_f32_16x16x32_bf16 v[78:81], v[114:117], v[118:121], v[78:81]
	ds_read_b128 v[230:233], v129 offset:16384
	ds_read_b128 v[234:237], v129 offset:22528
	ds_read_b128 v[90:93], v129 offset:18432
	ds_read_b128 v[94:97], v129 offset:20480
	s_waitcnt lgkmcnt(9)
	v_mfma_f32_16x16x32_bf16 v[74:77], v[166:169], v[118:121], v[74:77]
	s_waitcnt lgkmcnt(8)
	v_mfma_f32_16x16x32_bf16 v[70:73], v[170:173], v[118:121], v[70:73]
	s_waitcnt lgkmcnt(7)
	v_mfma_f32_16x16x32_bf16 v[66:69], v[174:177], v[118:121], v[66:69]
	s_waitcnt lgkmcnt(6)
	v_mfma_f32_16x16x32_bf16 v[62:65], v[114:117], v[238:241], v[62:65]
	v_mfma_f32_16x16x32_bf16 v[58:61], v[166:169], v[238:241], v[58:61]
	v_mfma_f32_16x16x32_bf16 v[54:57], v[170:173], v[238:241], v[54:57]
	v_mfma_f32_16x16x32_bf16 v[50:53], v[174:177], v[238:241], v[50:53]
	ds_read_b128 v[238:241], v128 offset:2048
	s_waitcnt lgkmcnt(6)
	v_mfma_f32_16x16x32_bf16 v[218:221], v[114:117], v[242:245], v[46:49]
	v_mfma_f32_16x16x32_bf16 v[222:225], v[166:169], v[242:245], v[42:45]
	v_mfma_f32_16x16x32_bf16 v[226:229], v[170:173], v[242:245], v[38:41]
	v_mfma_f32_16x16x32_bf16 v[118:121], v[174:177], v[242:245], v[34:37]
	s_nop 2
	ds_read_b128 v[34:37], v128
	ds_read_b128 v[242:245], v128 offset:4096
	s_waitcnt lgkmcnt(7)
	v_mfma_f32_16x16x32_bf16 v[114:117], v[114:117], v[246:249], v[30:33]
	v_mfma_f32_16x16x32_bf16 v[166:169], v[166:169], v[246:249], v[26:29]
	v_mfma_f32_16x16x32_bf16 v[170:173], v[170:173], v[246:249], v[22:25]
	v_mfma_f32_16x16x32_bf16 v[18:21], v[174:177], v[246:249], v[18:21]
	ds_read_b128 v[246:249], v128 offset:6144
	s_waitcnt lgkmcnt(2)
	v_mfma_f32_16x16x32_bf16 v[22:25], v[230:233], v[34:37], v[78:81]
	v_mfma_f32_16x16x32_bf16 v[26:29], v[90:93], v[34:37], v[74:77]
	v_mfma_f32_16x16x32_bf16 v[30:33], v[94:97], v[34:37], v[70:73]
	v_mfma_f32_16x16x32_bf16 v[34:37], v[234:237], v[34:37], v[66:69]
	v_mfma_f32_16x16x32_bf16 v[38:41], v[230:233], v[238:241], v[62:65]
	v_mfma_f32_16x16x32_bf16 v[42:45], v[90:93], v[238:241], v[58:61]
	v_mfma_f32_16x16x32_bf16 v[46:49], v[94:97], v[238:241], v[54:57]
	v_mfma_f32_16x16x32_bf16 v[50:53], v[234:237], v[238:241], v[50:53]
	s_waitcnt lgkmcnt(1)
	v_mfma_f32_16x16x32_bf16 v[54:57], v[230:233], v[242:245], v[218:221]
	v_mfma_f32_16x16x32_bf16 v[58:61], v[90:93], v[242:245], v[222:225]
	v_mfma_f32_16x16x32_bf16 v[62:65], v[94:97], v[242:245], v[226:229]
	v_mfma_f32_16x16x32_bf16 v[66:69], v[234:237], v[242:245], v[118:121]
	s_waitcnt lgkmcnt(0)
	v_mfma_f32_16x16x32_bf16 v[70:73], v[230:233], v[246:249], v[114:117]
	v_mfma_f32_16x16x32_bf16 v[74:77], v[90:93], v[246:249], v[166:169]
	v_mfma_f32_16x16x32_bf16 v[78:81], v[94:97], v[246:249], v[170:173]
	v_mfma_f32_16x16x32_bf16 v[18:21], v[234:237], v[246:249], v[18:21]
	s_cbranch_vccnz .LBB0_82
	s_waitcnt vmcnt(0)
	ds_write_b16 v130, v2 offset:36864
	ds_write_b16_d16_hi v130, v2 offset:36992
	ds_write_b16 v131, v3 offset:36864
	ds_write_b16_d16_hi v132, v3 offset:36864
	ds_write_b16 v133, v4 offset:36864
	ds_write_b16_d16_hi v134, v4 offset:36864
	ds_write_b16 v135, v5 offset:36864
	ds_write_b16_d16_hi v136, v5 offset:36864
	ds_write_b16 v137, v6 offset:36864
	ds_write_b16_d16_hi v137, v6 offset:36992
	ds_write_b16 v138, v7 offset:36864
	ds_write_b16_d16_hi v139, v7 offset:36864
	ds_write_b16 v140, v8 offset:36864
	ds_write_b16_d16_hi v141, v8 offset:36864
	ds_write_b16 v142, v9 offset:36864
	ds_write_b16_d16_hi v143, v9 offset:36864
	ds_write_b16 v144, v10 offset:36864
	ds_write_b16_d16_hi v144, v10 offset:36992
	ds_write_b16 v145, v11 offset:36864
	ds_write_b16_d16_hi v154, v11 offset:36864
	ds_write_b16 v155, v12 offset:36864
	ds_write_b16_d16_hi v156, v12 offset:36864
	ds_write_b16 v157, v13 offset:36864
	ds_write_b16_d16_hi v158, v13 offset:36864
	ds_write_b16 v159, v14 offset:36864
	ds_write_b16_d16_hi v159, v14 offset:36992
	ds_write_b16 v160, v15 offset:36864
	ds_write_b16_d16_hi v161, v15 offset:36864
	ds_write_b16 v162, v16 offset:36864
	ds_write_b16_d16_hi v163, v16 offset:36864
	ds_write_b16 v164, v17 offset:36864
	ds_write_b16_d16_hi v165, v17 offset:36864

.LBB0_87:
	s_andn2_b64 vcc, exec, s[40:41]
	s_waitcnt lgkmcnt(6)
	v_mfma_f32_16x16x32_bf16 v[22:25], v[106:109], v[110:113], v[22:25]
	ds_read_b128 v[222:225], v129 offset:53248
	ds_read_b128 v[226:229], v129 offset:59392
	ds_read_b128 v[90:93], v129 offset:55296
	ds_read_b128 v[94:97], v129 offset:57344
	s_waitcnt lgkmcnt(9)
	v_mfma_f32_16x16x32_bf16 v[26:29], v[114:117], v[110:113], v[26:29]
	s_waitcnt lgkmcnt(8)
	v_mfma_f32_16x16x32_bf16 v[30:33], v[118:121], v[110:113], v[30:33]
	s_waitcnt lgkmcnt(7)
	v_mfma_f32_16x16x32_bf16 v[34:37], v[166:169], v[110:113], v[34:37]
	s_waitcnt lgkmcnt(6)
	v_mfma_f32_16x16x32_bf16 v[38:41], v[106:109], v[238:241], v[38:41]
	v_mfma_f32_16x16x32_bf16 v[42:45], v[114:117], v[238:241], v[42:45]
	v_mfma_f32_16x16x32_bf16 v[46:49], v[118:121], v[238:241], v[46:49]
	v_mfma_f32_16x16x32_bf16 v[50:53], v[166:169], v[238:241], v[50:53]
	ds_read_b128 v[238:241], v128 offset:38912
	s_waitcnt lgkmcnt(6)
	v_mfma_f32_16x16x32_bf16 v[170:173], v[106:109], v[242:245], v[54:57]
	v_mfma_f32_16x16x32_bf16 v[174:177], v[114:117], v[242:245], v[58:61]
	v_mfma_f32_16x16x32_bf16 v[218:221], v[118:121], v[242:245], v[62:65]
	v_mfma_f32_16x16x32_bf16 v[110:113], v[166:169], v[242:245], v[66:69]
	s_nop 2
	ds_read_b128 v[54:57], v128 offset:36864
	ds_read_b128 v[242:245], v128 offset:40960
	s_waitcnt lgkmcnt(7)
	v_mfma_f32_16x16x32_bf16 v[106:109], v[106:109], v[246:249], v[70:73]
	v_mfma_f32_16x16x32_bf16 v[114:117], v[114:117], v[246:249], v[74:77]
	v_mfma_f32_16x16x32_bf16 v[118:121], v[118:121], v[246:249], v[78:81]
	v_mfma_f32_16x16x32_bf16 v[18:21], v[166:169], v[246:249], v[18:21]
	ds_read_b128 v[246:249], v128 offset:43008
	s_waitcnt lgkmcnt(2)
	v_mfma_f32_16x16x32_bf16 v[78:81], v[222:225], v[54:57], v[22:25]
	v_mfma_f32_16x16x32_bf16 v[74:77], v[90:93], v[54:57], v[26:29]
	v_mfma_f32_16x16x32_bf16 v[70:73], v[94:97], v[54:57], v[30:33]
	v_mfma_f32_16x16x32_bf16 v[66:69], v[226:229], v[54:57], v[34:37]
	v_mfma_f32_16x16x32_bf16 v[62:65], v[222:225], v[238:241], v[38:41]
	v_mfma_f32_16x16x32_bf16 v[58:61], v[90:93], v[238:241], v[42:45]
	v_mfma_f32_16x16x32_bf16 v[54:57], v[94:97], v[238:241], v[46:49]
	v_mfma_f32_16x16x32_bf16 v[50:53], v[226:229], v[238:241], v[50:53]
	s_waitcnt lgkmcnt(1)
	v_mfma_f32_16x16x32_bf16 v[34:37], v[226:229], v[242:245], v[110:113]
	v_mfma_f32_16x16x32_bf16 v[46:49], v[222:225], v[242:245], v[170:173]
	v_mfma_f32_16x16x32_bf16 v[42:45], v[90:93], v[242:245], v[174:177]
	v_mfma_f32_16x16x32_bf16 v[38:41], v[94:97], v[242:245], v[218:221]
	s_waitcnt lgkmcnt(0)
	v_mfma_f32_16x16x32_bf16 v[30:33], v[222:225], v[246:249], v[106:109]
	v_mfma_f32_16x16x32_bf16 v[26:29], v[90:93], v[246:249], v[114:117]
	v_mfma_f32_16x16x32_bf16 v[22:25], v[94:97], v[246:249], v[118:121]
	v_mfma_f32_16x16x32_bf16 v[18:21], v[226:229], v[246:249], v[18:21]
	s_cbranch_vccnz .LBB0_75
	s_waitcnt vmcnt(0)
	ds_write_b16 v130, v2
	ds_write_b16_d16_hi v130, v2 offset:128
	ds_write_b16 v131, v3
	ds_write_b16_d16_hi v132, v3
	ds_write_b16 v133, v4
	ds_write_b16_d16_hi v134, v4
	ds_write_b16 v135, v5
	ds_write_b16_d16_hi v136, v5
	ds_write_b16 v137, v6
	ds_write_b16_d16_hi v137, v6 offset:128
	ds_write_b16 v138, v7
	ds_write_b16_d16_hi v139, v7
	ds_write_b16 v140, v8
	ds_write_b16_d16_hi v141, v8
	ds_write_b16 v142, v9
	ds_write_b16_d16_hi v143, v9
	ds_write_b16 v144, v10
	ds_write_b16_d16_hi v144, v10 offset:128
	ds_write_b16 v145, v11
	ds_write_b16_d16_hi v154, v11
	ds_write_b16 v155, v12
	ds_write_b16_d16_hi v156, v12
	ds_write_b16 v157, v13
	ds_write_b16_d16_hi v158, v13
	ds_write_b16 v159, v14
	ds_write_b16_d16_hi v159, v14 offset:128
	ds_write_b16 v160, v15
	ds_write_b16_d16_hi v161, v15
	ds_write_b16 v162, v16
	ds_write_b16_d16_hi v163, v16
	ds_write_b16 v164, v17
	ds_write_b16_d16_hi v165, v17
	s_branch .LBB0_75
